# combo11 with the deferred PG / P1 row loops run by the 7-tile CUs before their in-proj tiles instead of after them
# speedup vs baseline: 1.0135x; 1.0111x over previous
.LBB0_267:
	s_and_b64 vcc, exec, s[0:1]
	s_cbranch_vccz .LBB0_420
	s_cmpk_lg_u32 s36, 0x100
	s_cbranch_scc1 .Ldpg_skip
	s_cmpk_lt_u32 s57, 0xa0
	s_cbranch_scc1 .Ldpg_skip
	v_readlane_b32 s10, v254, 62
	s_nop 3
	s_cmp_eq_u32 s10, 0
	s_cbranch_scc1 .Ldpg_skip
	v_mov_b32_e32 v0, v167
	v_readlane_b32 s1, v251, 14
	v_readfirstlane_b32 s0, v0
	s_ashr_i32 s0, s0, 6
	s_add_i32 s0, s0, s1
	s_add_i32 s0, s0, 0xfffffb00
	s_mov_b32 s56, 0x800000
	v_readlane_b32 s10, v254, 62
	s_add_i32 s10, s10, -1
	v_readlane_b32 s11, v254, 63
	s_mov_b32 s14, s10
	s_mulk_i32 s10, 0xc00
	s_ashr_i32 s11, s10, 31
	s_lshl_b64 s[10:11], s[10:11], 2
	s_add_u32 s12, s4, s10
	v_and_b32_e32 v2, 63, v0
	s_addc_u32 s13, s5, s11
	v_lshlrev_b32_e32 v0, 4, v2
	s_waitcnt lgkmcnt(0)
	v_mov_b32_e32 v1, v157
	v_lshlrev_b32_e32 v156, 3, v2
	v_lshl_add_u64 v[2:3], s[12:13], 0, v[0:1]
	s_mov_b64 s[12:13], 0x2a12000
	v_cmp_lt_i32_e32 vcc, v188, v187
	s_waitcnt vmcnt(0)
	v_lshl_add_u64 v[8:9], v[2:3], 0, s[12:13]
	s_mov_b32 s10, s14
	v_cndmask_b32_e32 v2, v185, v188, vcc
	v_cmp_lt_i32_e32 vcc, v189, v187
	v_lshlrev_b32_e32 v44, 2, v2
	v_cndmask_b32_e32 v2, v185, v189, vcc
	v_cmp_lt_i32_e32 vcc, v190, v187
	v_lshlrev_b32_e32 v45, 2, v2
	s_ashr_i32 s15, s14, 31
	v_cndmask_b32_e32 v2, v185, v190, vcc
	v_cmp_lt_i32_e32 vcc, v191, v187
	v_lshlrev_b32_e32 v46, 2, v2
	v_cndmask_b32_e32 v2, v185, v191, vcc
	v_cmp_lt_i32_e32 vcc, v250, v187
	s_lshl_b64 s[10:11], s[14:15], 23
	v_readlane_b32 s84, v254, 4
	v_lshlrev_b32_e32 v47, 2, v2
	v_cndmask_b32_e32 v2, v185, v250, vcc
	v_cmp_lt_i32_e32 vcc, v184, v187
	v_readlane_b32 s12, v251, 0
	v_readlane_b32 s85, v254, 5
	v_lshlrev_b32_e32 v48, 2, v2
	v_cndmask_b32_e32 v2, v185, v184, vcc
	v_readlane_b32 s16, v251, 4
	v_readlane_b32 s17, v251, 5
	v_readlane_b32 s18, v251, 6
	v_readlane_b32 s19, v251, 7
	v_lshl_add_u64 v[4:5], s[84:85], 0, v[0:1]
	v_lshl_add_u64 v[6:7], s[82:83], 0, v[156:157]
	v_lshlrev_b32_e32 v49, 2, v2
	v_lshl_add_u64 v[10:11], s[16:17], 0, v[0:1]
	v_lshl_add_u64 v[12:13], s[18:19], 0, v[156:157]
	v_readlane_b32 s86, v254, 6
	v_readlane_b32 s87, v254, 7
	v_readlane_b32 s88, v254, 8
	v_readlane_b32 s89, v254, 9
	v_readlane_b32 s90, v254, 10
	v_readlane_b32 s91, v254, 11
	v_readlane_b32 s92, v254, 12
	v_readlane_b32 s93, v254, 13
	v_readlane_b32 s94, v254, 14
	v_readlane_b32 s95, v254, 15
	v_readlane_b32 s96, v254, 16
	v_readlane_b32 s97, v254, 17
	v_readlane_b32 s98, v254, 18
	v_readlane_b32 s99, v254, 19
	v_readlane_b32 s13, v251, 1
	v_readlane_b32 s14, v251, 2
	v_readlane_b32 s15, v251, 3
	global_load_dwordx4 v[64:67], v[8:9], off
	global_load_dwordx4 v[68:71], v[8:9], off offset:1024
	global_load_dwordx4 v[72:75], v[8:9], off offset:2048
	global_load_dwordx4 v[76:79], v[8:9], off offset:3072
	global_load_dwordx4 v[80:83], v[10:11], off
	global_load_dwordx4 v[84:87], v[10:11], off offset:1024
	global_load_dwordx4 v[88:91], v[10:11], off offset:2048
	global_load_dwordx4 v[92:95], v[10:11], off offset:3072
	s_ashr_i32 s13, s0, 31
	s_mov_b32 s12, s0
	s_lshl_b64 s[14:15], s[12:13], 11
	s_lshl_b64 s[12:13], s[12:13], 10
	s_add_u32 s12, s12, s10
	s_addc_u32 s13, s13, s11
	s_lshl_b64 s[12:13], s[12:13], 2
	v_lshl_add_u64 v[40:41], v[4:5], 0, s[12:13]
	v_lshl_add_u64 v[42:43], v[12:13], 0, s[12:13]
	v_lshl_add_u64 v[2:3], v[6:7], 0, s[14:15]
	global_load_dwordx2 v[112:113], v[42:43], off
	global_load_dwordx2 v[114:115], v[42:43], off offset:512
	global_load_dwordx2 v[116:117], v[42:43], off offset:1024
	global_load_dwordx2 v[118:119], v[42:43], off offset:1536
	global_load_dwordx2 v[120:121], v[2:3], off
	global_load_dwordx2 v[122:123], v[2:3], off offset:512
	global_load_dwordx2 v[124:125], v[2:3], off offset:1024
	global_load_dwordx2 v[126:127], v[2:3], off offset:1536
	global_load_dwordx4 v[96:99], v[40:41], off
	global_load_dwordx4 v[100:103], v[40:41], off offset:1024
	global_load_dwordx4 v[104:107], v[40:41], off offset:2048
	global_load_dwordx4 v[108:111], v[40:41], off offset:3072
	s_waitcnt vmcnt(0)

.Ldp1_skip:
	s_waitcnt vmcnt(0)
	v_readlane_b32 s0, v251, 22
	v_mov_b32_e32 v5, v167
	v_readlane_b32 s1, v251, 23
	s_andn2_b64 vcc, exec, s[0:1]
	v_readfirstlane_b32 s10, v5
	s_cbranch_vccnz .LBB0_419
	v_lshlrev_b32_e32 v0, 4, v5
	s_waitcnt lgkmcnt(0)
	v_add_u32_e32 v1, 0x2000, v0
	v_ashrrev_i32_e32 v2, 31, v1
	v_lshrrev_b32_e32 v2, 22, v2
	v_add_u32_e32 v2, v1, v2
	v_ashrrev_i32_e32 v4, 10, v2
	v_mul_i32_i24_e32 v2, 0x400, v4
	v_sub_u32_e32 v1, v1, v2
	v_lshrrev_b32_e32 v2, 4, v1
	v_bitop3_b32 v1, v2, v1, 32 bitop3:0x6c
	v_ashrrev_i32_e32 v2, 31, v1
	v_readlane_b32 s0, v254, 62
	v_lshrrev_b32_e32 v2, 26, v2
	v_readlane_b32 s1, v254, 63
	v_add_u32_e32 v2, v1, v2
	v_lshlrev_b32_e32 v3, 3, v4
	s_ashr_i32 s1, s0, 31
	v_ashrrev_i32_e32 v6, 6, v2
	v_and_b32_e32 v3, -16, v3
	s_lshl_b64 s[0:1], s[0:1], 24
	v_readlane_b32 s8, v251, 12
	v_add_u32_e32 v3, v6, v3
	s_add_u32 s14, s8, s0
	v_and_b32_e32 v7, 3, v6
	s_mov_b32 s0, 0x1fffe0
	s_waitcnt vmcnt(0)
	v_lshrrev_b32_e32 v8, 2, v3
	v_lshlrev_b32_e32 v9, 1, v3
	v_and_b32_e32 v2, 0xc0, v2
	v_and_or_b32 v7, v3, s0, v7
	v_and_b32_e32 v8, 4, v8
	v_and_b32_e32 v9, 24, v9
	v_sub_u32_e32 v1, v1, v2
	v_mov_b32_e32 v12, 1
	v_or3_b32 v8, v7, v8, v9
	v_lshlrev_b32_e32 v7, 5, v4
	v_ashrrev_i16_sdwa v1, v12, sext(v1) dst_sel:DWORD dst_unused:UNUSED_PAD src0_sel:DWORD src1_sel:BYTE_0
	v_and_b32_e32 v9, 32, v7
	v_bfe_i32 v7, v1, 0, 16
	v_add_lshl_u32 v1, v9, v7, 1
	v_lshl_add_u32 v148, v8, 11, v1
	v_lshl_add_u32 v150, v3, 11, v1
	v_bfe_i32 v1, v5, 27, 1
	v_lshrrev_b32_e32 v1, 22, v1
	v_add_u32_e32 v1, v0, v1
	v_and_b32_e32 v1, 0xfffffc00, v1
	v_sub_u32_e32 v0, v0, v1
	v_lshrrev_b32_e32 v1, 4, v0
	v_ashrrev_i32_e32 v2, 31, v5
	v_bitop3_b32 v0, v1, v0, 32 bitop3:0x6c
	v_lshrrev_b32_e32 v2, 26, v2
	v_ashrrev_i32_e32 v1, 31, v0
	v_add_u32_e32 v2, v5, v2
	v_lshrrev_b32_e32 v1, 26, v1
	v_ashrrev_i32_e32 v9, 6, v2
	v_add_u32_e32 v1, v0, v1
	v_lshlrev_b32_e32 v2, 3, v9
	v_ashrrev_i32_e32 v8, 6, v1
	v_and_b32_e32 v2, -16, v2
	v_add_u32_e32 v2, v8, v2
	v_and_b32_e32 v3, 3, v8
	v_lshrrev_b32_e32 v10, 2, v2
	v_lshlrev_b32_e32 v11, 1, v2
	v_and_b32_e32 v1, 0xc0, v1
	v_readlane_b32 s9, v251, 13
	v_and_or_b32 v3, v2, s0, v3
	v_and_b32_e32 v10, 4, v10
	v_and_b32_e32 v11, 24, v11
	v_sub_u32_e32 v0, v0, v1
	s_addc_u32 s15, s9, s1
	s_ashr_i32 s11, s10, 6
	v_or3_b32 v3, v3, v10, v11
	v_lshlrev_b32_e32 v10, 5, v9
	v_ashrrev_i16_sdwa v0, v12, sext(v0) dst_sel:DWORD dst_unused:UNUSED_PAD src0_sel:DWORD src1_sel:BYTE_0
	s_lshl_b32 s16, s11, 10
	v_and_b32_e32 v11, 32, v10
	v_bfe_i32 v10, v0, 0, 16
	v_add_lshl_u32 v0, v11, v10, 1
	s_add_i32 s17, s16, 16
	v_readlane_b32 s0, v253, 56
	v_lshl_add_u32 v152, v3, 11, v0
	s_add_i32 m0, s17, 0x10000
	v_readlane_b32 s1, v253, 57
	s_ashr_i32 s12, s10, 8
	v_lshl_add_u32 v154, v2, 11, v0
	v_mov_b32_e32 v155, v157
	v_mov_b32_e32 v151, v157
	s_nop 0
	global_load_lds_dwordx4 v152, s[0:1]
	s_add_i32 m0, s17, 0x12000
	s_nop 0
	global_load_lds_dwordx4 v148, s[0:1]
	v_readlane_b32 s0, v253, 54
	s_add_i32 m0, s17, 0x14000
	v_readlane_b32 s1, v253, 55
	s_nop 4
	global_load_lds_dwordx4 v152, s[0:1]
	s_add_i32 m0, s17, 0x16000
	s_nop 0
	global_load_lds_dwordx4 v148, s[0:1]
	v_readlane_b32 s0, v253, 51
	v_readlane_b32 s1, v253, 52
	s_add_u32 s8, s14, s0
	s_addc_u32 s9, s15, s1
	s_add_i32 s18, s17, 0x2000
	s_mov_b32 m0, s17
	s_add_u32 s0, s8, 0x40000
	global_load_lds_dwordx4 v154, s[8:9]
	s_mov_b32 m0, s18
	s_addc_u32 s1, s9, 0
	s_add_i32 s19, s17, 0x4000
	global_load_lds_dwordx4 v150, s[8:9]
	s_mov_b32 m0, s19
	s_add_i32 s20, s17, 0x6000
	global_load_lds_dwordx4 v154, s[0:1]
	s_mov_b32 m0, s20
	s_cmp_eq_u32 s12, 1
	global_load_lds_dwordx4 v150, s[0:1]
	v_lshl_add_u64 v[0:1], s[8:9], 0, v[154:155]
	s_cselect_b64 s[0:1], -1, 0
	s_cmp_lg_u32 s12, 1
	v_lshl_add_u64 v[2:3], s[8:9], 0, v[150:151]
	s_cbranch_scc1 .LBB0_271
	s_barrier
